# P5 merge epilogue rewritten: all gate/gy tile loads streamed through dead fragment registers (22 in flight) instead of 4 serialized rounds; same math
# speedup vs baseline: 1.0010x; 1.0010x over previous
.LBB0_793:
	s_lshl_b32 s2, s47, 8
	v_readlane_b32 s3, v253, 62
	s_add_i32 s2, s2, s3
	v_add_u32_e32 v250, s2, v194
	s_lshl_b32 s2, s46, 8
	v_readlane_b32 s3, v254, 18
	s_or_b32 s2, s2, s3
	v_lshl_add_u32 v251, v195, 3, s2
	v_lshlrev_b32_e32 v251, 1, v251
	v_lshl_add_u32 v248, v250, 13, v251
	v_lshl_add_u32 v249, v250, 11, v251
	s_lshl_b32 s0, s45, 11
	s_add_u32 s0, s4, s0
	s_addc_u32 s1, s5, 0
	s_mov_b64 s[56:57], s[0:1]
	s_mov_b64 s[82:83], s[6:7]
	s_add_u32 s58, s0, 0x20000
	s_addc_u32 s59, s1, 0
	s_add_u32 s84, s6, 0x8000
	s_addc_u32 s85, s7, 0
	s_add_u32 s60, s0, 0x40000
	s_addc_u32 s61, s1, 0
	s_add_u32 s86, s6, 0x10000
	s_addc_u32 s87, s7, 0
	s_add_u32 s62, s0, 0x60000
	s_addc_u32 s63, s1, 0
	s_add_u32 s88, s6, 0x18000
	s_addc_u32 s89, s7, 0
	s_add_u32 s64, s0, 0x100000
	s_addc_u32 s65, s1, 0
	s_add_u32 s90, s6, 0x40000
	s_addc_u32 s91, s7, 0
	s_add_u32 s66, s0, 0x120000
	s_addc_u32 s67, s1, 0
	s_add_u32 s92, s6, 0x48000
	s_addc_u32 s93, s7, 0
	s_add_u32 s68, s0, 0x140000
	s_addc_u32 s69, s1, 0
	s_add_u32 s94, s6, 0x50000
	s_addc_u32 s95, s7, 0
	s_add_u32 s70, s0, 0x160000
	s_addc_u32 s71, s1, 0
	s_add_u32 s96, s6, 0x58000
	s_addc_u32 s97, s7, 0
	s_cmp_lg_u32 s45, 0
	s_cbranch_scc0 .Lm_first
	global_load_dwordx4 v[130:133], v248, s[56:57]
	global_load_dwordx4 v[134:137], v249, s[82:83]
	global_load_dwordx4 v[138:141], v248, s[56:57] offset:256
	global_load_dwordx4 v[142:145], v249, s[82:83] offset:256
	global_load_dwordx4 v[146:149], v248, s[58:59]
	global_load_dwordx4 v[150:153], v249, s[84:85]
	global_load_dwordx4 v[164:167], v248, s[58:59] offset:256
	global_load_dwordx4 v[168:171], v249, s[84:85] offset:256
	global_load_dwordx4 v[172:175], v248, s[60:61]
	global_load_dwordx4 v[180:183], v249, s[86:87]
	global_load_dwordx4 v[184:187], v248, s[60:61] offset:256
	global_load_dwordx4 v[188:191], v249, s[86:87] offset:256
	global_load_dwordx4 v[198:201], v248, s[62:63]
	global_load_dwordx4 v[212:215], v249, s[88:89]
	global_load_dwordx4 v[216:219], v248, s[62:63] offset:256
	global_load_dwordx4 v[220:223], v249, s[88:89] offset:256
	global_load_dwordx4 v[224:227], v248, s[64:65]
	global_load_dwordx4 v[228:231], v249, s[90:91]
	global_load_dwordx4 v[232:235], v248, s[64:65] offset:256
	global_load_dwordx4 v[236:239], v249, s[90:91] offset:256
	global_load_dwordx4 v[240:243], v248, s[66:67]
	global_load_dwordx4 v[244:247], v249, s[92:93]
	s_waitcnt vmcnt(20)
	v_lshlrev_b32_e32 v250, 16, v130
	v_lshlrev_b32_e32 v251, 16, v134
	v_and_b32_e32 v130, 0xffff0000, v130
	v_and_b32_e32 v134, 0xffff0000, v134
	v_lshlrev_b32_e32 v192, 16, v131
	v_lshlrev_b32_e32 v193, 16, v135
	v_and_b32_e32 v131, 0xffff0000, v131
	v_and_b32_e32 v135, 0xffff0000, v135
	v_fmac_f32_e32 v251, v126, v250
	v_fmac_f32_e32 v134, v127, v130
	v_fmac_f32_e32 v193, v128, v192
	v_fmac_f32_e32 v135, v129, v131
	v_cvt_pk_bf16_f32 v134, v251, v134
	v_cvt_pk_bf16_f32 v135, v193, v135
	v_lshlrev_b32_e32 v250, 16, v132
	v_lshlrev_b32_e32 v251, 16, v136
	v_and_b32_e32 v132, 0xffff0000, v132
	v_and_b32_e32 v136, 0xffff0000, v136
	v_lshlrev_b32_e32 v192, 16, v133
	v_lshlrev_b32_e32 v193, 16, v137
	v_and_b32_e32 v133, 0xffff0000, v133
	v_and_b32_e32 v137, 0xffff0000, v137
	v_fmac_f32_e32 v251, v122, v250
	v_fmac_f32_e32 v136, v123, v132
	v_fmac_f32_e32 v193, v124, v192
	v_fmac_f32_e32 v137, v125, v133
	v_cvt_pk_bf16_f32 v136, v251, v136
	v_cvt_pk_bf16_f32 v137, v193, v137
	global_store_dwordx4 v249, v[134:137], s[82:83]
	global_load_dwordx4 v[130:133], v248, s[66:67] offset:256
	s_waitcnt vmcnt(20)
	v_lshlrev_b32_e32 v250, 16, v138
	v_lshlrev_b32_e32 v251, 16, v142
	v_and_b32_e32 v138, 0xffff0000, v138
	v_and_b32_e32 v142, 0xffff0000, v142
	v_lshlrev_b32_e32 v192, 16, v139
	v_lshlrev_b32_e32 v193, 16, v143
	v_and_b32_e32 v139, 0xffff0000, v139
	v_and_b32_e32 v143, 0xffff0000, v143
	v_fmac_f32_e32 v251, v114, v250
	v_fmac_f32_e32 v142, v115, v138
	v_fmac_f32_e32 v193, v116, v192
	v_fmac_f32_e32 v143, v117, v139
	v_cvt_pk_bf16_f32 v142, v251, v142
	v_cvt_pk_bf16_f32 v143, v193, v143
	v_lshlrev_b32_e32 v250, 16, v140
	v_lshlrev_b32_e32 v251, 16, v144
	v_and_b32_e32 v140, 0xffff0000, v140
	v_and_b32_e32 v144, 0xffff0000, v144
	v_lshlrev_b32_e32 v192, 16, v141
	v_lshlrev_b32_e32 v193, 16, v145
	v_and_b32_e32 v141, 0xffff0000, v141
	v_and_b32_e32 v145, 0xffff0000, v145
	v_fmac_f32_e32 v251, v106, v250
	v_fmac_f32_e32 v144, v107, v140
	v_fmac_f32_e32 v193, v108, v192
	v_fmac_f32_e32 v145, v109, v141
	v_cvt_pk_bf16_f32 v144, v251, v144
	v_cvt_pk_bf16_f32 v145, v193, v145
	global_store_dwordx4 v249, v[142:145], s[82:83] offset:256
	global_load_dwordx4 v[138:141], v249, s[92:93] offset:256
	global_load_dwordx4 v[134:137], v248, s[68:69]
	s_waitcnt vmcnt(21)
	v_lshlrev_b32_e32 v250, 16, v146
	v_lshlrev_b32_e32 v251, 16, v150
	v_and_b32_e32 v146, 0xffff0000, v146
	v_and_b32_e32 v150, 0xffff0000, v150
	v_lshlrev_b32_e32 v192, 16, v147
	v_lshlrev_b32_e32 v193, 16, v151
	v_and_b32_e32 v147, 0xffff0000, v147
	v_and_b32_e32 v151, 0xffff0000, v151
	v_fmac_f32_e32 v251, v118, v250
	v_fmac_f32_e32 v150, v119, v146
	v_fmac_f32_e32 v193, v120, v192
	v_fmac_f32_e32 v151, v121, v147
	v_cvt_pk_bf16_f32 v150, v251, v150
	v_cvt_pk_bf16_f32 v151, v193, v151
	v_lshlrev_b32_e32 v250, 16, v148
	v_lshlrev_b32_e32 v251, 16, v152
	v_and_b32_e32 v148, 0xffff0000, v148
	v_and_b32_e32 v152, 0xffff0000, v152
	v_lshlrev_b32_e32 v192, 16, v149
	v_lshlrev_b32_e32 v193, 16, v153
	v_and_b32_e32 v149, 0xffff0000, v149
	v_and_b32_e32 v153, 0xffff0000, v153
	v_fmac_f32_e32 v251, v110, v250
	v_fmac_f32_e32 v152, v111, v148
	v_fmac_f32_e32 v193, v112, v192
	v_fmac_f32_e32 v153, v113, v149
	v_cvt_pk_bf16_f32 v152, v251, v152
	v_cvt_pk_bf16_f32 v153, v193, v153
	global_store_dwordx4 v249, v[150:153], s[84:85]
	global_load_dwordx4 v[146:149], v249, s[94:95]
	global_load_dwordx4 v[142:145], v248, s[68:69] offset:256
	s_waitcnt vmcnt(22)
	v_lshlrev_b32_e32 v250, 16, v164
	v_lshlrev_b32_e32 v251, 16, v168
	v_and_b32_e32 v164, 0xffff0000, v164
	v_and_b32_e32 v168, 0xffff0000, v168
	v_lshlrev_b32_e32 v192, 16, v165
	v_lshlrev_b32_e32 v193, 16, v169
	v_and_b32_e32 v165, 0xffff0000, v165
	v_and_b32_e32 v169, 0xffff0000, v169
	v_fmac_f32_e32 v251, v102, v250
	v_fmac_f32_e32 v168, v103, v164
	v_fmac_f32_e32 v193, v104, v192
	v_fmac_f32_e32 v169, v105, v165
	v_cvt_pk_bf16_f32 v168, v251, v168
	v_cvt_pk_bf16_f32 v169, v193, v169
	v_lshlrev_b32_e32 v250, 16, v166
	v_lshlrev_b32_e32 v251, 16, v170
	v_and_b32_e32 v166, 0xffff0000, v166
	v_and_b32_e32 v170, 0xffff0000, v170
	v_lshlrev_b32_e32 v192, 16, v167
	v_lshlrev_b32_e32 v193, 16, v171
	v_and_b32_e32 v167, 0xffff0000, v167
	v_and_b32_e32 v171, 0xffff0000, v171
	v_fmac_f32_e32 v251, v98, v250
	v_fmac_f32_e32 v170, v99, v166
	v_fmac_f32_e32 v193, v100, v192
	v_fmac_f32_e32 v171, v101, v167
	v_cvt_pk_bf16_f32 v170, v251, v170
	v_cvt_pk_bf16_f32 v171, v193, v171
	global_store_dwordx4 v249, v[168:171], s[84:85] offset:256
	global_load_dwordx4 v[164:167], v249, s[94:95] offset:256
	global_load_dwordx4 v[150:153], v248, s[70:71]
	s_waitcnt vmcnt(23)
	v_lshlrev_b32_e32 v250, 16, v172
	v_lshlrev_b32_e32 v251, 16, v180
	v_and_b32_e32 v172, 0xffff0000, v172
	v_and_b32_e32 v180, 0xffff0000, v180
	v_lshlrev_b32_e32 v192, 16, v173
	v_lshlrev_b32_e32 v193, 16, v181
	v_and_b32_e32 v173, 0xffff0000, v173
	v_and_b32_e32 v181, 0xffff0000, v181
	v_fmac_f32_e32 v251, v94, v250
	v_fmac_f32_e32 v180, v95, v172
	v_fmac_f32_e32 v193, v96, v192
	v_fmac_f32_e32 v181, v97, v173
	v_cvt_pk_bf16_f32 v180, v251, v180
	v_cvt_pk_bf16_f32 v181, v193, v181
	v_lshlrev_b32_e32 v250, 16, v174
	v_lshlrev_b32_e32 v251, 16, v182
	v_and_b32_e32 v174, 0xffff0000, v174
	v_and_b32_e32 v182, 0xffff0000, v182
	v_lshlrev_b32_e32 v192, 16, v175
	v_lshlrev_b32_e32 v193, 16, v183
	v_and_b32_e32 v175, 0xffff0000, v175
	v_and_b32_e32 v183, 0xffff0000, v183
	v_fmac_f32_e32 v251, v90, v250
	v_fmac_f32_e32 v182, v91, v174
	v_fmac_f32_e32 v193, v92, v192
	v_fmac_f32_e32 v183, v93, v175
	v_cvt_pk_bf16_f32 v182, v251, v182
	v_cvt_pk_bf16_f32 v183, v193, v183
	global_store_dwordx4 v249, v[180:183], s[86:87]
	global_load_dwordx4 v[172:175], v249, s[96:97]
	global_load_dwordx4 v[168:171], v248, s[70:71] offset:256
	s_waitcnt vmcnt(24)
	v_lshlrev_b32_e32 v250, 16, v184
	v_lshlrev_b32_e32 v251, 16, v188
	v_and_b32_e32 v184, 0xffff0000, v184
	v_and_b32_e32 v188, 0xffff0000, v188
	v_lshlrev_b32_e32 v192, 16, v185
	v_lshlrev_b32_e32 v193, 16, v189
	v_and_b32_e32 v185, 0xffff0000, v185
	v_and_b32_e32 v189, 0xffff0000, v189
	v_fmac_f32_e32 v251, v82, v250
	v_fmac_f32_e32 v188, v83, v184
	v_fmac_f32_e32 v193, v84, v192
	v_fmac_f32_e32 v189, v85, v185
	v_cvt_pk_bf16_f32 v188, v251, v188
	v_cvt_pk_bf16_f32 v189, v193, v189
	v_lshlrev_b32_e32 v250, 16, v186
	v_lshlrev_b32_e32 v251, 16, v190
	v_and_b32_e32 v186, 0xffff0000, v186
	v_and_b32_e32 v190, 0xffff0000, v190
	v_lshlrev_b32_e32 v192, 16, v187
	v_lshlrev_b32_e32 v193, 16, v191
	v_and_b32_e32 v187, 0xffff0000, v187
	v_and_b32_e32 v191, 0xffff0000, v191
	v_fmac_f32_e32 v251, v74, v250
	v_fmac_f32_e32 v190, v75, v186
	v_fmac_f32_e32 v193, v76, v192
	v_fmac_f32_e32 v191, v77, v187
	v_cvt_pk_bf16_f32 v190, v251, v190
	v_cvt_pk_bf16_f32 v191, v193, v191
	global_store_dwordx4 v249, v[188:191], s[86:87] offset:256
	global_load_dwordx4 v[184:187], v249, s[96:97] offset:256
	s_waitcnt vmcnt(24)
	v_lshlrev_b32_e32 v250, 16, v198
	v_lshlrev_b32_e32 v251, 16, v212
	v_and_b32_e32 v198, 0xffff0000, v198
	v_and_b32_e32 v212, 0xffff0000, v212
	v_lshlrev_b32_e32 v192, 16, v199
	v_lshlrev_b32_e32 v193, 16, v213
	v_and_b32_e32 v199, 0xffff0000, v199
	v_and_b32_e32 v213, 0xffff0000, v213
	v_fmac_f32_e32 v251, v86, v250
	v_fmac_f32_e32 v212, v87, v198
	v_fmac_f32_e32 v193, v88, v192
	v_fmac_f32_e32 v213, v89, v199
	v_cvt_pk_bf16_f32 v212, v251, v212
	v_cvt_pk_bf16_f32 v213, v193, v213
	v_lshlrev_b32_e32 v250, 16, v200
	v_lshlrev_b32_e32 v251, 16, v214
	v_and_b32_e32 v200, 0xffff0000, v200
	v_and_b32_e32 v214, 0xffff0000, v214
	v_lshlrev_b32_e32 v192, 16, v201
	v_lshlrev_b32_e32 v193, 16, v215
	v_and_b32_e32 v201, 0xffff0000, v201
	v_and_b32_e32 v215, 0xffff0000, v215
	v_fmac_f32_e32 v251, v78, v250
	v_fmac_f32_e32 v214, v79, v200
	v_fmac_f32_e32 v193, v80, v192
	v_fmac_f32_e32 v215, v81, v201
	v_cvt_pk_bf16_f32 v214, v251, v214
	v_cvt_pk_bf16_f32 v215, v193, v215
	global_store_dwordx4 v249, v[212:215], s[88:89]
	s_waitcnt vmcnt(23)
	v_lshlrev_b32_e32 v250, 16, v216
	v_lshlrev_b32_e32 v251, 16, v220
	v_and_b32_e32 v216, 0xffff0000, v216
	v_and_b32_e32 v220, 0xffff0000, v220
	v_lshlrev_b32_e32 v192, 16, v217
	v_lshlrev_b32_e32 v193, 16, v221
	v_and_b32_e32 v217, 0xffff0000, v217
	v_and_b32_e32 v221, 0xffff0000, v221
	v_fmac_f32_e32 v251, v70, v250
	v_fmac_f32_e32 v220, v71, v216
	v_fmac_f32_e32 v193, v72, v192
	v_fmac_f32_e32 v221, v73, v217
	v_cvt_pk_bf16_f32 v220, v251, v220
	v_cvt_pk_bf16_f32 v221, v193, v221
	v_lshlrev_b32_e32 v250, 16, v218
	v_lshlrev_b32_e32 v251, 16, v222
	v_and_b32_e32 v218, 0xffff0000, v218
	v_and_b32_e32 v222, 0xffff0000, v222
	v_lshlrev_b32_e32 v192, 16, v219
	v_lshlrev_b32_e32 v193, 16, v223
	v_and_b32_e32 v219, 0xffff0000, v219
	v_and_b32_e32 v223, 0xffff0000, v223
	v_fmac_f32_e32 v251, v66, v250
	v_fmac_f32_e32 v222, v67, v218
	v_fmac_f32_e32 v193, v68, v192
	v_fmac_f32_e32 v223, v69, v219
	v_cvt_pk_bf16_f32 v222, v251, v222
	v_cvt_pk_bf16_f32 v223, v193, v223
	global_store_dwordx4 v249, v[220:223], s[88:89] offset:256
	s_waitcnt vmcnt(22)
	v_lshlrev_b32_e32 v250, 16, v224
	v_lshlrev_b32_e32 v251, 16, v228
	v_and_b32_e32 v224, 0xffff0000, v224
	v_and_b32_e32 v228, 0xffff0000, v228
	v_lshlrev_b32_e32 v192, 16, v225
	v_lshlrev_b32_e32 v193, 16, v229
	v_and_b32_e32 v225, 0xffff0000, v225
	v_and_b32_e32 v229, 0xffff0000, v229
	v_fmac_f32_e32 v251, v62, v250
	v_fmac_f32_e32 v228, v63, v224
	v_fmac_f32_e32 v193, v64, v192
	v_fmac_f32_e32 v229, v65, v225
	v_cvt_pk_bf16_f32 v228, v251, v228
	v_cvt_pk_bf16_f32 v229, v193, v229
	v_lshlrev_b32_e32 v250, 16, v226
	v_lshlrev_b32_e32 v251, 16, v230
	v_and_b32_e32 v226, 0xffff0000, v226
	v_and_b32_e32 v230, 0xffff0000, v230
	v_lshlrev_b32_e32 v192, 16, v227
	v_lshlrev_b32_e32 v193, 16, v231
	v_and_b32_e32 v227, 0xffff0000, v227
	v_and_b32_e32 v231, 0xffff0000, v231
	v_fmac_f32_e32 v251, v58, v250
	v_fmac_f32_e32 v230, v59, v226
	v_fmac_f32_e32 v193, v60, v192
	v_fmac_f32_e32 v231, v61, v227
	v_cvt_pk_bf16_f32 v230, v251, v230
	v_cvt_pk_bf16_f32 v231, v193, v231
	global_store_dwordx4 v249, v[228:231], s[90:91]
	s_waitcnt vmcnt(21)
	v_lshlrev_b32_e32 v250, 16, v232
	v_lshlrev_b32_e32 v251, 16, v236
	v_and_b32_e32 v232, 0xffff0000, v232
	v_and_b32_e32 v236, 0xffff0000, v236
	v_lshlrev_b32_e32 v192, 16, v233
	v_lshlrev_b32_e32 v193, 16, v237
	v_and_b32_e32 v233, 0xffff0000, v233
	v_and_b32_e32 v237, 0xffff0000, v237
	v_fmac_f32_e32 v251, v50, v250
	v_fmac_f32_e32 v236, v51, v232
	v_fmac_f32_e32 v193, v52, v192
	v_fmac_f32_e32 v237, v53, v233
	v_cvt_pk_bf16_f32 v236, v251, v236
	v_cvt_pk_bf16_f32 v237, v193, v237
	v_lshlrev_b32_e32 v250, 16, v234
	v_lshlrev_b32_e32 v251, 16, v238
	v_and_b32_e32 v234, 0xffff0000, v234
	v_and_b32_e32 v238, 0xffff0000, v238
	v_lshlrev_b32_e32 v192, 16, v235
	v_lshlrev_b32_e32 v193, 16, v239
	v_and_b32_e32 v235, 0xffff0000, v235
	v_and_b32_e32 v239, 0xffff0000, v239
	v_fmac_f32_e32 v251, v42, v250
	v_fmac_f32_e32 v238, v43, v234
	v_fmac_f32_e32 v193, v44, v192
	v_fmac_f32_e32 v239, v45, v235
	v_cvt_pk_bf16_f32 v238, v251, v238
	v_cvt_pk_bf16_f32 v239, v193, v239
	global_store_dwordx4 v249, v[236:239], s[90:91] offset:256
	s_waitcnt vmcnt(20)
	v_lshlrev_b32_e32 v250, 16, v240
	v_lshlrev_b32_e32 v251, 16, v244
	v_and_b32_e32 v240, 0xffff0000, v240
	v_and_b32_e32 v244, 0xffff0000, v244
	v_lshlrev_b32_e32 v192, 16, v241
	v_lshlrev_b32_e32 v193, 16, v245
	v_and_b32_e32 v241, 0xffff0000, v241
	v_and_b32_e32 v245, 0xffff0000, v245
	v_fmac_f32_e32 v251, v54, v250
	v_fmac_f32_e32 v244, v55, v240
	v_fmac_f32_e32 v193, v56, v192
	v_fmac_f32_e32 v245, v57, v241
	v_cvt_pk_bf16_f32 v244, v251, v244
	v_cvt_pk_bf16_f32 v245, v193, v245
	v_lshlrev_b32_e32 v250, 16, v242
	v_lshlrev_b32_e32 v251, 16, v246
	v_and_b32_e32 v242, 0xffff0000, v242
	v_and_b32_e32 v246, 0xffff0000, v246
	v_lshlrev_b32_e32 v192, 16, v243
	v_lshlrev_b32_e32 v193, 16, v247
	v_and_b32_e32 v243, 0xffff0000, v243
	v_and_b32_e32 v247, 0xffff0000, v247
	v_fmac_f32_e32 v251, v46, v250
	v_fmac_f32_e32 v246, v47, v242
	v_fmac_f32_e32 v193, v48, v192
	v_fmac_f32_e32 v247, v49, v243
	v_cvt_pk_bf16_f32 v246, v251, v246
	v_cvt_pk_bf16_f32 v247, v193, v247
	global_store_dwordx4 v249, v[244:247], s[92:93]
	s_waitcnt vmcnt(17)
	v_lshlrev_b32_e32 v250, 16, v130
	v_lshlrev_b32_e32 v251, 16, v138
	v_and_b32_e32 v130, 0xffff0000, v130
	v_and_b32_e32 v138, 0xffff0000, v138
	v_lshlrev_b32_e32 v192, 16, v131
	v_lshlrev_b32_e32 v193, 16, v139
	v_and_b32_e32 v131, 0xffff0000, v131
	v_and_b32_e32 v139, 0xffff0000, v139
	v_fmac_f32_e32 v251, v38, v250
	v_fmac_f32_e32 v138, v39, v130
	v_fmac_f32_e32 v193, v40, v192
	v_fmac_f32_e32 v139, v41, v131
	v_cvt_pk_bf16_f32 v138, v251, v138
	v_cvt_pk_bf16_f32 v139, v193, v139
	v_lshlrev_b32_e32 v250, 16, v132
	v_lshlrev_b32_e32 v251, 16, v140
	v_and_b32_e32 v132, 0xffff0000, v132
	v_and_b32_e32 v140, 0xffff0000, v140
	v_lshlrev_b32_e32 v192, 16, v133
	v_lshlrev_b32_e32 v193, 16, v141
	v_and_b32_e32 v133, 0xffff0000, v133
	v_and_b32_e32 v141, 0xffff0000, v141
	v_fmac_f32_e32 v251, v34, v250
	v_fmac_f32_e32 v140, v35, v132
	v_fmac_f32_e32 v193, v36, v192
	v_fmac_f32_e32 v141, v37, v133
	v_cvt_pk_bf16_f32 v140, v251, v140
	v_cvt_pk_bf16_f32 v141, v193, v141
	global_store_dwordx4 v249, v[138:141], s[92:93] offset:256
	s_waitcnt vmcnt(15)
	v_lshlrev_b32_e32 v250, 16, v134
	v_lshlrev_b32_e32 v251, 16, v146
	v_and_b32_e32 v134, 0xffff0000, v134
	v_and_b32_e32 v146, 0xffff0000, v146
	v_lshlrev_b32_e32 v192, 16, v135
	v_lshlrev_b32_e32 v193, 16, v147
	v_and_b32_e32 v135, 0xffff0000, v135
	v_and_b32_e32 v147, 0xffff0000, v147
	v_fmac_f32_e32 v251, v30, v250
	v_fmac_f32_e32 v146, v31, v134
	v_fmac_f32_e32 v193, v32, v192
	v_fmac_f32_e32 v147, v33, v135
	v_cvt_pk_bf16_f32 v146, v251, v146
	v_cvt_pk_bf16_f32 v147, v193, v147
	v_lshlrev_b32_e32 v250, 16, v136
	v_lshlrev_b32_e32 v251, 16, v148
	v_and_b32_e32 v136, 0xffff0000, v136
	v_and_b32_e32 v148, 0xffff0000, v148
	v_lshlrev_b32_e32 v192, 16, v137
	v_lshlrev_b32_e32 v193, 16, v149
	v_and_b32_e32 v137, 0xffff0000, v137
	v_and_b32_e32 v149, 0xffff0000, v149
	v_fmac_f32_e32 v251, v26, v250
	v_fmac_f32_e32 v148, v27, v136
	v_fmac_f32_e32 v193, v28, v192
	v_fmac_f32_e32 v149, v29, v137
	v_cvt_pk_bf16_f32 v148, v251, v148
	v_cvt_pk_bf16_f32 v149, v193, v149
	global_store_dwordx4 v249, v[146:149], s[94:95]
	s_waitcnt vmcnt(13)
	v_lshlrev_b32_e32 v250, 16, v142
	v_lshlrev_b32_e32 v251, 16, v164
	v_and_b32_e32 v142, 0xffff0000, v142
	v_and_b32_e32 v164, 0xffff0000, v164
	v_lshlrev_b32_e32 v192, 16, v143
	v_lshlrev_b32_e32 v193, 16, v165
	v_and_b32_e32 v143, 0xffff0000, v143
	v_and_b32_e32 v165, 0xffff0000, v165
	v_fmac_f32_e32 v251, v18, v250
	v_fmac_f32_e32 v164, v19, v142
	v_fmac_f32_e32 v193, v20, v192
	v_fmac_f32_e32 v165, v21, v143
	v_cvt_pk_bf16_f32 v164, v251, v164
	v_cvt_pk_bf16_f32 v165, v193, v165
	v_lshlrev_b32_e32 v250, 16, v144
	v_lshlrev_b32_e32 v251, 16, v166
	v_and_b32_e32 v144, 0xffff0000, v144
	v_and_b32_e32 v166, 0xffff0000, v166
	v_lshlrev_b32_e32 v192, 16, v145
	v_lshlrev_b32_e32 v193, 16, v167
	v_and_b32_e32 v145, 0xffff0000, v145
	v_and_b32_e32 v167, 0xffff0000, v167
	v_fmac_f32_e32 v251, v10, v250
	v_fmac_f32_e32 v166, v11, v144
	v_fmac_f32_e32 v193, v12, v192
	v_fmac_f32_e32 v167, v13, v145
	v_cvt_pk_bf16_f32 v166, v251, v166
	v_cvt_pk_bf16_f32 v167, v193, v167
	global_store_dwordx4 v249, v[164:167], s[94:95] offset:256
	s_waitcnt vmcnt(11)
	v_lshlrev_b32_e32 v250, 16, v150
	v_lshlrev_b32_e32 v251, 16, v172
	v_and_b32_e32 v150, 0xffff0000, v150
	v_and_b32_e32 v172, 0xffff0000, v172
	v_lshlrev_b32_e32 v192, 16, v151
	v_lshlrev_b32_e32 v193, 16, v173
	v_and_b32_e32 v151, 0xffff0000, v151
	v_and_b32_e32 v173, 0xffff0000, v173
	v_fmac_f32_e32 v251, v22, v250
	v_fmac_f32_e32 v172, v23, v150
	v_fmac_f32_e32 v193, v24, v192
	v_fmac_f32_e32 v173, v25, v151
	v_cvt_pk_bf16_f32 v172, v251, v172
	v_cvt_pk_bf16_f32 v173, v193, v173
	v_lshlrev_b32_e32 v250, 16, v152
	v_lshlrev_b32_e32 v251, 16, v174
	v_and_b32_e32 v152, 0xffff0000, v152
	v_and_b32_e32 v174, 0xffff0000, v174
	v_lshlrev_b32_e32 v192, 16, v153
	v_lshlrev_b32_e32 v193, 16, v175
	v_and_b32_e32 v153, 0xffff0000, v153
	v_and_b32_e32 v175, 0xffff0000, v175
	v_fmac_f32_e32 v251, v14, v250
	v_fmac_f32_e32 v174, v15, v152
	v_fmac_f32_e32 v193, v16, v192
	v_fmac_f32_e32 v175, v17, v153
	v_cvt_pk_bf16_f32 v174, v251, v174
	v_cvt_pk_bf16_f32 v175, v193, v175
	global_store_dwordx4 v249, v[172:175], s[96:97]
	s_waitcnt vmcnt(9)
	v_lshlrev_b32_e32 v250, 16, v168
	v_lshlrev_b32_e32 v251, 16, v184
	v_and_b32_e32 v168, 0xffff0000, v168
	v_and_b32_e32 v184, 0xffff0000, v184
	v_lshlrev_b32_e32 v192, 16, v169
	v_lshlrev_b32_e32 v193, 16, v185
	v_and_b32_e32 v169, 0xffff0000, v169
	v_and_b32_e32 v185, 0xffff0000, v185
	v_fmac_f32_e32 v251, v6, v250
	v_fmac_f32_e32 v184, v7, v168
	v_fmac_f32_e32 v193, v8, v192
	v_fmac_f32_e32 v185, v9, v169
	v_cvt_pk_bf16_f32 v184, v251, v184
	v_cvt_pk_bf16_f32 v185, v193, v185
	v_lshlrev_b32_e32 v250, 16, v170
	v_lshlrev_b32_e32 v251, 16, v186
	v_and_b32_e32 v170, 0xffff0000, v170
	v_and_b32_e32 v186, 0xffff0000, v186
	v_lshlrev_b32_e32 v192, 16, v171
	v_lshlrev_b32_e32 v193, 16, v187
	v_and_b32_e32 v171, 0xffff0000, v171
	v_and_b32_e32 v187, 0xffff0000, v187
	v_fmac_f32_e32 v251, v2, v250
	v_fmac_f32_e32 v186, v3, v170
	v_fmac_f32_e32 v193, v4, v192
	v_fmac_f32_e32 v187, v5, v171
	v_cvt_pk_bf16_f32 v186, v251, v186
	v_cvt_pk_bf16_f32 v187, v193, v187
	global_store_dwordx4 v249, v[184:187], s[96:97] offset:256
	s_branch .Lm_done
.Lm_first:
	global_load_dwordx4 v[130:133], v248, s[56:57]
	global_load_dwordx4 v[134:137], v248, s[56:57] offset:256
	global_load_dwordx4 v[138:141], v248, s[58:59]
	global_load_dwordx4 v[142:145], v248, s[58:59] offset:256
	global_load_dwordx4 v[146:149], v248, s[60:61]
	global_load_dwordx4 v[150:153], v248, s[60:61] offset:256
	global_load_dwordx4 v[164:167], v248, s[62:63]
	global_load_dwordx4 v[168:171], v248, s[62:63] offset:256
	global_load_dwordx4 v[172:175], v248, s[64:65]
	global_load_dwordx4 v[180:183], v248, s[64:65] offset:256
	global_load_dwordx4 v[184:187], v248, s[66:67]
	global_load_dwordx4 v[188:191], v248, s[66:67] offset:256
	global_load_dwordx4 v[198:201], v248, s[68:69]
	global_load_dwordx4 v[212:215], v248, s[68:69] offset:256
	global_load_dwordx4 v[216:219], v248, s[70:71]
	global_load_dwordx4 v[220:223], v248, s[70:71] offset:256
	s_waitcnt vmcnt(15)
	v_lshlrev_b32_e32 v250, 16, v130
	v_and_b32_e32 v130, 0xffff0000, v130
	v_lshlrev_b32_e32 v192, 16, v131
	v_and_b32_e32 v131, 0xffff0000, v131
	v_fma_f32 v250, v126, v250, 0
	v_fma_f32 v130, v127, v130, 0
	v_fma_f32 v192, v128, v192, 0
	v_fma_f32 v131, v129, v131, 0
	v_cvt_pk_bf16_f32 v130, v250, v130
	v_cvt_pk_bf16_f32 v131, v192, v131
	v_lshlrev_b32_e32 v250, 16, v132
	v_and_b32_e32 v132, 0xffff0000, v132
	v_lshlrev_b32_e32 v192, 16, v133
	v_and_b32_e32 v133, 0xffff0000, v133
	v_fma_f32 v250, v122, v250, 0
	v_fma_f32 v132, v123, v132, 0
	v_fma_f32 v192, v124, v192, 0
	v_fma_f32 v133, v125, v133, 0
	v_cvt_pk_bf16_f32 v132, v250, v132
	v_cvt_pk_bf16_f32 v133, v192, v133
	global_store_dwordx4 v249, v[130:133], s[82:83]
	s_waitcnt vmcnt(15)
	v_lshlrev_b32_e32 v250, 16, v134
	v_and_b32_e32 v134, 0xffff0000, v134
	v_lshlrev_b32_e32 v192, 16, v135
	v_and_b32_e32 v135, 0xffff0000, v135
	v_fma_f32 v250, v114, v250, 0
	v_fma_f32 v134, v115, v134, 0
	v_fma_f32 v192, v116, v192, 0
	v_fma_f32 v135, v117, v135, 0
	v_cvt_pk_bf16_f32 v134, v250, v134
	v_cvt_pk_bf16_f32 v135, v192, v135
	v_lshlrev_b32_e32 v250, 16, v136
	v_and_b32_e32 v136, 0xffff0000, v136
	v_lshlrev_b32_e32 v192, 16, v137
	v_and_b32_e32 v137, 0xffff0000, v137
	v_fma_f32 v250, v106, v250, 0
	v_fma_f32 v136, v107, v136, 0
	v_fma_f32 v192, v108, v192, 0
	v_fma_f32 v137, v109, v137, 0
	v_cvt_pk_bf16_f32 v136, v250, v136
	v_cvt_pk_bf16_f32 v137, v192, v137
	global_store_dwordx4 v249, v[134:137], s[82:83] offset:256
	s_waitcnt vmcnt(15)
	v_lshlrev_b32_e32 v250, 16, v138
	v_and_b32_e32 v138, 0xffff0000, v138
	v_lshlrev_b32_e32 v192, 16, v139
	v_and_b32_e32 v139, 0xffff0000, v139
	v_fma_f32 v250, v118, v250, 0
	v_fma_f32 v138, v119, v138, 0
	v_fma_f32 v192, v120, v192, 0
	v_fma_f32 v139, v121, v139, 0
	v_cvt_pk_bf16_f32 v138, v250, v138
	v_cvt_pk_bf16_f32 v139, v192, v139
	v_lshlrev_b32_e32 v250, 16, v140
	v_and_b32_e32 v140, 0xffff0000, v140
	v_lshlrev_b32_e32 v192, 16, v141
	v_and_b32_e32 v141, 0xffff0000, v141
	v_fma_f32 v250, v110, v250, 0
	v_fma_f32 v140, v111, v140, 0
	v_fma_f32 v192, v112, v192, 0
	v_fma_f32 v141, v113, v141, 0
	v_cvt_pk_bf16_f32 v140, v250, v140
	v_cvt_pk_bf16_f32 v141, v192, v141
	global_store_dwordx4 v249, v[138:141], s[84:85]
	s_waitcnt vmcnt(15)
	v_lshlrev_b32_e32 v250, 16, v142
	v_and_b32_e32 v142, 0xffff0000, v142
	v_lshlrev_b32_e32 v192, 16, v143
	v_and_b32_e32 v143, 0xffff0000, v143
	v_fma_f32 v250, v102, v250, 0
	v_fma_f32 v142, v103, v142, 0
	v_fma_f32 v192, v104, v192, 0
	v_fma_f32 v143, v105, v143, 0
	v_cvt_pk_bf16_f32 v142, v250, v142
	v_cvt_pk_bf16_f32 v143, v192, v143
	v_lshlrev_b32_e32 v250, 16, v144
	v_and_b32_e32 v144, 0xffff0000, v144
	v_lshlrev_b32_e32 v192, 16, v145
	v_and_b32_e32 v145, 0xffff0000, v145
	v_fma_f32 v250, v98, v250, 0
	v_fma_f32 v144, v99, v144, 0
	v_fma_f32 v192, v100, v192, 0
	v_fma_f32 v145, v101, v145, 0
	v_cvt_pk_bf16_f32 v144, v250, v144
	v_cvt_pk_bf16_f32 v145, v192, v145
	global_store_dwordx4 v249, v[142:145], s[84:85] offset:256
	s_waitcnt vmcnt(15)
	v_lshlrev_b32_e32 v250, 16, v146
	v_and_b32_e32 v146, 0xffff0000, v146
	v_lshlrev_b32_e32 v192, 16, v147
	v_and_b32_e32 v147, 0xffff0000, v147
	v_fma_f32 v250, v94, v250, 0
	v_fma_f32 v146, v95, v146, 0
	v_fma_f32 v192, v96, v192, 0
	v_fma_f32 v147, v97, v147, 0
	v_cvt_pk_bf16_f32 v146, v250, v146
	v_cvt_pk_bf16_f32 v147, v192, v147
	v_lshlrev_b32_e32 v250, 16, v148
	v_and_b32_e32 v148, 0xffff0000, v148
	v_lshlrev_b32_e32 v192, 16, v149
	v_and_b32_e32 v149, 0xffff0000, v149
	v_fma_f32 v250, v90, v250, 0
	v_fma_f32 v148, v91, v148, 0
	v_fma_f32 v192, v92, v192, 0
	v_fma_f32 v149, v93, v149, 0
	v_cvt_pk_bf16_f32 v148, v250, v148
	v_cvt_pk_bf16_f32 v149, v192, v149
	global_store_dwordx4 v249, v[146:149], s[86:87]
	s_waitcnt vmcnt(15)
	v_lshlrev_b32_e32 v250, 16, v150
	v_and_b32_e32 v150, 0xffff0000, v150
	v_lshlrev_b32_e32 v192, 16, v151
	v_and_b32_e32 v151, 0xffff0000, v151
	v_fma_f32 v250, v82, v250, 0
	v_fma_f32 v150, v83, v150, 0
	v_fma_f32 v192, v84, v192, 0
	v_fma_f32 v151, v85, v151, 0
	v_cvt_pk_bf16_f32 v150, v250, v150
	v_cvt_pk_bf16_f32 v151, v192, v151
	v_lshlrev_b32_e32 v250, 16, v152
	v_and_b32_e32 v152, 0xffff0000, v152
	v_lshlrev_b32_e32 v192, 16, v153
	v_and_b32_e32 v153, 0xffff0000, v153
	v_fma_f32 v250, v74, v250, 0
	v_fma_f32 v152, v75, v152, 0
	v_fma_f32 v192, v76, v192, 0
	v_fma_f32 v153, v77, v153, 0
	v_cvt_pk_bf16_f32 v152, v250, v152
	v_cvt_pk_bf16_f32 v153, v192, v153
	global_store_dwordx4 v249, v[150:153], s[86:87] offset:256
	s_waitcnt vmcnt(15)
	v_lshlrev_b32_e32 v250, 16, v164
	v_and_b32_e32 v164, 0xffff0000, v164
	v_lshlrev_b32_e32 v192, 16, v165
	v_and_b32_e32 v165, 0xffff0000, v165
	v_fma_f32 v250, v86, v250, 0
	v_fma_f32 v164, v87, v164, 0
	v_fma_f32 v192, v88, v192, 0
	v_fma_f32 v165, v89, v165, 0
	v_cvt_pk_bf16_f32 v164, v250, v164
	v_cvt_pk_bf16_f32 v165, v192, v165
	v_lshlrev_b32_e32 v250, 16, v166
	v_and_b32_e32 v166, 0xffff0000, v166
	v_lshlrev_b32_e32 v192, 16, v167
	v_and_b32_e32 v167, 0xffff0000, v167
	v_fma_f32 v250, v78, v250, 0
	v_fma_f32 v166, v79, v166, 0
	v_fma_f32 v192, v80, v192, 0
	v_fma_f32 v167, v81, v167, 0
	v_cvt_pk_bf16_f32 v166, v250, v166
	v_cvt_pk_bf16_f32 v167, v192, v167
	global_store_dwordx4 v249, v[164:167], s[88:89]
	s_waitcnt vmcnt(15)
	v_lshlrev_b32_e32 v250, 16, v168
	v_and_b32_e32 v168, 0xffff0000, v168
	v_lshlrev_b32_e32 v192, 16, v169
	v_and_b32_e32 v169, 0xffff0000, v169
	v_fma_f32 v250, v70, v250, 0
	v_fma_f32 v168, v71, v168, 0
	v_fma_f32 v192, v72, v192, 0
	v_fma_f32 v169, v73, v169, 0
	v_cvt_pk_bf16_f32 v168, v250, v168
	v_cvt_pk_bf16_f32 v169, v192, v169
	v_lshlrev_b32_e32 v250, 16, v170
	v_and_b32_e32 v170, 0xffff0000, v170
	v_lshlrev_b32_e32 v192, 16, v171
	v_and_b32_e32 v171, 0xffff0000, v171
	v_fma_f32 v250, v66, v250, 0
	v_fma_f32 v170, v67, v170, 0
	v_fma_f32 v192, v68, v192, 0
	v_fma_f32 v171, v69, v171, 0
	v_cvt_pk_bf16_f32 v170, v250, v170
	v_cvt_pk_bf16_f32 v171, v192, v171
	global_store_dwordx4 v249, v[168:171], s[88:89] offset:256
	s_waitcnt vmcnt(15)
	v_lshlrev_b32_e32 v250, 16, v172
	v_and_b32_e32 v172, 0xffff0000, v172
	v_lshlrev_b32_e32 v192, 16, v173
	v_and_b32_e32 v173, 0xffff0000, v173
	v_fma_f32 v250, v62, v250, 0
	v_fma_f32 v172, v63, v172, 0
	v_fma_f32 v192, v64, v192, 0
	v_fma_f32 v173, v65, v173, 0
	v_cvt_pk_bf16_f32 v172, v250, v172
	v_cvt_pk_bf16_f32 v173, v192, v173
	v_lshlrev_b32_e32 v250, 16, v174
	v_and_b32_e32 v174, 0xffff0000, v174
	v_lshlrev_b32_e32 v192, 16, v175
	v_and_b32_e32 v175, 0xffff0000, v175
	v_fma_f32 v250, v58, v250, 0
	v_fma_f32 v174, v59, v174, 0
	v_fma_f32 v192, v60, v192, 0
	v_fma_f32 v175, v61, v175, 0
	v_cvt_pk_bf16_f32 v174, v250, v174
	v_cvt_pk_bf16_f32 v175, v192, v175
	global_store_dwordx4 v249, v[172:175], s[90:91]
	s_waitcnt vmcnt(15)
	v_lshlrev_b32_e32 v250, 16, v180
	v_and_b32_e32 v180, 0xffff0000, v180
	v_lshlrev_b32_e32 v192, 16, v181
	v_and_b32_e32 v181, 0xffff0000, v181
	v_fma_f32 v250, v50, v250, 0
	v_fma_f32 v180, v51, v180, 0
	v_fma_f32 v192, v52, v192, 0
	v_fma_f32 v181, v53, v181, 0
	v_cvt_pk_bf16_f32 v180, v250, v180
	v_cvt_pk_bf16_f32 v181, v192, v181
	v_lshlrev_b32_e32 v250, 16, v182
	v_and_b32_e32 v182, 0xffff0000, v182
	v_lshlrev_b32_e32 v192, 16, v183
	v_and_b32_e32 v183, 0xffff0000, v183
	v_fma_f32 v250, v42, v250, 0
	v_fma_f32 v182, v43, v182, 0
	v_fma_f32 v192, v44, v192, 0
	v_fma_f32 v183, v45, v183, 0
	v_cvt_pk_bf16_f32 v182, v250, v182
	v_cvt_pk_bf16_f32 v183, v192, v183
	global_store_dwordx4 v249, v[180:183], s[90:91] offset:256
	s_waitcnt vmcnt(15)
	v_lshlrev_b32_e32 v250, 16, v184
	v_and_b32_e32 v184, 0xffff0000, v184
	v_lshlrev_b32_e32 v192, 16, v185
	v_and_b32_e32 v185, 0xffff0000, v185
	v_fma_f32 v250, v54, v250, 0
	v_fma_f32 v184, v55, v184, 0
	v_fma_f32 v192, v56, v192, 0
	v_fma_f32 v185, v57, v185, 0
	v_cvt_pk_bf16_f32 v184, v250, v184
	v_cvt_pk_bf16_f32 v185, v192, v185
	v_lshlrev_b32_e32 v250, 16, v186
	v_and_b32_e32 v186, 0xffff0000, v186
	v_lshlrev_b32_e32 v192, 16, v187
	v_and_b32_e32 v187, 0xffff0000, v187
	v_fma_f32 v250, v46, v250, 0
	v_fma_f32 v186, v47, v186, 0
	v_fma_f32 v192, v48, v192, 0
	v_fma_f32 v187, v49, v187, 0
	v_cvt_pk_bf16_f32 v186, v250, v186
	v_cvt_pk_bf16_f32 v187, v192, v187
	global_store_dwordx4 v249, v[184:187], s[92:93]
	s_waitcnt vmcnt(15)
	v_lshlrev_b32_e32 v250, 16, v188
	v_and_b32_e32 v188, 0xffff0000, v188
	v_lshlrev_b32_e32 v192, 16, v189
	v_and_b32_e32 v189, 0xffff0000, v189
	v_fma_f32 v250, v38, v250, 0
	v_fma_f32 v188, v39, v188, 0
	v_fma_f32 v192, v40, v192, 0
	v_fma_f32 v189, v41, v189, 0
	v_cvt_pk_bf16_f32 v188, v250, v188
	v_cvt_pk_bf16_f32 v189, v192, v189
	v_lshlrev_b32_e32 v250, 16, v190
	v_and_b32_e32 v190, 0xffff0000, v190
	v_lshlrev_b32_e32 v192, 16, v191
	v_and_b32_e32 v191, 0xffff0000, v191
	v_fma_f32 v250, v34, v250, 0
	v_fma_f32 v190, v35, v190, 0
	v_fma_f32 v192, v36, v192, 0
	v_fma_f32 v191, v37, v191, 0
	v_cvt_pk_bf16_f32 v190, v250, v190
	v_cvt_pk_bf16_f32 v191, v192, v191
	global_store_dwordx4 v249, v[188:191], s[92:93] offset:256
	s_waitcnt vmcnt(15)
	v_lshlrev_b32_e32 v250, 16, v198
	v_and_b32_e32 v198, 0xffff0000, v198
	v_lshlrev_b32_e32 v192, 16, v199
	v_and_b32_e32 v199, 0xffff0000, v199
	v_fma_f32 v250, v30, v250, 0
	v_fma_f32 v198, v31, v198, 0
	v_fma_f32 v192, v32, v192, 0
	v_fma_f32 v199, v33, v199, 0
	v_cvt_pk_bf16_f32 v198, v250, v198
	v_cvt_pk_bf16_f32 v199, v192, v199
	v_lshlrev_b32_e32 v250, 16, v200
	v_and_b32_e32 v200, 0xffff0000, v200
	v_lshlrev_b32_e32 v192, 16, v201
	v_and_b32_e32 v201, 0xffff0000, v201
	v_fma_f32 v250, v26, v250, 0
	v_fma_f32 v200, v27, v200, 0
	v_fma_f32 v192, v28, v192, 0
	v_fma_f32 v201, v29, v201, 0
	v_cvt_pk_bf16_f32 v200, v250, v200
	v_cvt_pk_bf16_f32 v201, v192, v201
	global_store_dwordx4 v249, v[198:201], s[94:95]
	s_waitcnt vmcnt(15)
	v_lshlrev_b32_e32 v250, 16, v212
	v_and_b32_e32 v212, 0xffff0000, v212
	v_lshlrev_b32_e32 v192, 16, v213
	v_and_b32_e32 v213, 0xffff0000, v213
	v_fma_f32 v250, v18, v250, 0
	v_fma_f32 v212, v19, v212, 0
	v_fma_f32 v192, v20, v192, 0
	v_fma_f32 v213, v21, v213, 0
	v_cvt_pk_bf16_f32 v212, v250, v212
	v_cvt_pk_bf16_f32 v213, v192, v213
	v_lshlrev_b32_e32 v250, 16, v214
	v_and_b32_e32 v214, 0xffff0000, v214
	v_lshlrev_b32_e32 v192, 16, v215
	v_and_b32_e32 v215, 0xffff0000, v215
	v_fma_f32 v250, v10, v250, 0
	v_fma_f32 v214, v11, v214, 0
	v_fma_f32 v192, v12, v192, 0
	v_fma_f32 v215, v13, v215, 0
	v_cvt_pk_bf16_f32 v214, v250, v214
	v_cvt_pk_bf16_f32 v215, v192, v215
	global_store_dwordx4 v249, v[212:215], s[94:95] offset:256
	s_waitcnt vmcnt(15)
	v_lshlrev_b32_e32 v250, 16, v216
	v_and_b32_e32 v216, 0xffff0000, v216
	v_lshlrev_b32_e32 v192, 16, v217
	v_and_b32_e32 v217, 0xffff0000, v217
	v_fma_f32 v250, v22, v250, 0
	v_fma_f32 v216, v23, v216, 0
	v_fma_f32 v192, v24, v192, 0
	v_fma_f32 v217, v25, v217, 0
	v_cvt_pk_bf16_f32 v216, v250, v216
	v_cvt_pk_bf16_f32 v217, v192, v217
	v_lshlrev_b32_e32 v250, 16, v218
	v_and_b32_e32 v218, 0xffff0000, v218
	v_lshlrev_b32_e32 v192, 16, v219
	v_and_b32_e32 v219, 0xffff0000, v219
	v_fma_f32 v250, v14, v250, 0
	v_fma_f32 v218, v15, v218, 0
	v_fma_f32 v192, v16, v192, 0
	v_fma_f32 v219, v17, v219, 0
	v_cvt_pk_bf16_f32 v218, v250, v218
	v_cvt_pk_bf16_f32 v219, v192, v219
	global_store_dwordx4 v249, v[216:219], s[96:97]
	s_waitcnt vmcnt(15)
	v_lshlrev_b32_e32 v250, 16, v220
	v_and_b32_e32 v220, 0xffff0000, v220
	v_lshlrev_b32_e32 v192, 16, v221
	v_and_b32_e32 v221, 0xffff0000, v221
	v_fma_f32 v250, v6, v250, 0
	v_fma_f32 v220, v7, v220, 0
	v_fma_f32 v192, v8, v192, 0
	v_fma_f32 v221, v9, v221, 0
	v_cvt_pk_bf16_f32 v220, v250, v220
	v_cvt_pk_bf16_f32 v221, v192, v221
	v_lshlrev_b32_e32 v250, 16, v222
	v_and_b32_e32 v222, 0xffff0000, v222
	v_lshlrev_b32_e32 v192, 16, v223
	v_and_b32_e32 v223, 0xffff0000, v223
	v_fma_f32 v250, v2, v250, 0
	v_fma_f32 v222, v3, v222, 0
	v_fma_f32 v192, v4, v192, 0
	v_fma_f32 v223, v5, v223, 0
	v_cvt_pk_bf16_f32 v222, v250, v222
	v_cvt_pk_bf16_f32 v223, v192, v223
	global_store_dwordx4 v249, v[220:223], s[96:97] offset:256
.Lm_done:
	s_andn2_b64 vcc, exec, s[42:43]
	s_mov_b64 s[0:1], -1
	s_cbranch_vccnz .LBB0_782
	s_and_b64 vcc, exec, s[40:41]
	s_cbranch_vccnz .LBB0_781
	s_barrier
	s_branch .LBB0_781
.LBB0_800:
	s_waitcnt vmcnt(0)
	v_readlane_b32 s35, v255, 24
	s_barrier
